# adds: out-projection (phase 5) GEMM mainloop also LDS-DMA staged; NSA selected-branch K/V tiles staged by LDS-DMA one step ahead instead of VGPR + ds_write
# speedup vs baseline: 1.0462x; 1.0151x over previous
; template <int MASK, int PASS>
; DI void run_tiles_b(Flash& st, const bf16x8 (&qf)[4], const BSrc& src, const int* list, int n, char* kvbuf, int qpos,
;                     int qmin_w, int qmax_w, const OnFn onfn, const float* lut, float bfar, float* imp_row, float rinv) {
;     TileRegsB RA, RB;
;     if (n > 0) tileb_issue(RA, src, list[0]);
;     if (n > 1) tileb_issue(RB, src, list[1]);
; DI void nsa_item(const Params& p, char* sm, bool dec, int b, int kvh, int q32) {
;     ...
;             const size_t hb = (size_t)(b * 2 + kvh) * 8192 * 64;
;             const BSrc bs{(const u16*)(p.ws + WS_KSB) + hb, (const u16*)(p.ws + WS_VSB) + hb, 8191};
;             run_tiles_b<0, 0>(st, qf, bs, list, ntile, sm + SM_KV, qpos, qmin_w, qmax_w, onf, lut, bfar, nullptr, 0.f);
.LBB0_1356:
	s_or_b64 exec, exec, s[0:1]
	s_waitcnt lgkmcnt(0)
	s_barrier
	ds_read_b32 v2, v3 offset:33404
	s_lshl_b32 s0, s83, 20
	v_readlane_b32 s1, v254, 48
	s_add_u32 s2, s1, s0
	v_readlane_b32 s1, v254, 49
	s_addc_u32 s3, s1, 0
	v_readlane_b32 s1, v254, 50
	s_add_u32 s16, s1, s0
	v_readlane_b32 s0, v254, 51
	s_waitcnt lgkmcnt(0)
	v_cmp_gt_i32_e32 vcc, 1, v2
	v_readfirstlane_b32 s20, v2
	s_addc_u32 s17, s0, 0
	s_and_b64 vcc, exec, vcc
	v_cmp_lt_i32_e64 s[0:1], 0, v2
	v_and_b32_e32 v120, 63, v0
	v_lshrrev_b32_e32 v126, 6, v0
	v_lshrrev_b32_e32 v121, 3, v120
	v_and_b32_e32 v122, 7, v120
	v_readfirstlane_b32 s52, v126
	v_lshrrev_b32_e32 v123, 1, v121
	v_xor_b32_e32 v124, v122, v123
	v_xor_b32_e32 v125, 4, v124
	v_lshl_add_u32 v118, v126, 4, v121
	v_add_u32_e32 v119, 8, v118
	v_lshlrev_b32_e32 v128, 4, v124
	v_mov_b32_e32 v129, 0
	v_lshl_add_u64 v[110:111], s[2:3], 0, v[128:129]
	v_lshlrev_b32_e32 v128, 4, v125
	v_lshl_add_u64 v[112:113], s[2:3], 0, v[128:129]
	v_lshlrev_b32_e32 v128, 4, v122
	v_lshl_add_u64 v[114:115], s[16:17], 0, v[128:129]
	s_lshl_b32 s24, s52, 11
	s_add_i32 s26, s24, 0x2000
	s_add_i32 s28, s24, 0x4000
	s_add_i32 s32, s24, 0x6000
	s_cbranch_vccnz .LBB0_1360
	ds_read_b32 v2, v3 offset:32768
	s_waitcnt lgkmcnt(0)
	v_add_u32_e32 v120, v2, v118
	v_add_u32_e32 v122, v2, v119
	v_med3_i32 v120, v120, 0, v214
	v_med3_i32 v122, v122, 0, v214
	v_lshlrev_b32_e32 v120, 7, v120
	v_lshlrev_b32_e32 v122, 7, v122
	v_mov_b32_e32 v121, 0
	v_mov_b32_e32 v123, 0
	v_lshl_add_u64 v[124:125], v[110:111], 0, v[120:121]
	v_lshl_add_u64 v[126:127], v[112:113], 0, v[122:123]
	v_lshl_add_u64 v[128:129], v[114:115], 0, v[120:121]
	v_lshl_add_u64 v[130:131], v[114:115], 0, v[122:123]
	s_mov_b32 m0, s24
	s_add_i32 s58, s24, 0x400
	global_load_lds_dwordx4 v[124:125], off
	s_mov_b32 m0, s58
	s_nop 0
	global_load_lds_dwordx4 v[126:127], off
	s_mov_b32 m0, s26
	s_add_i32 s58, s26, 0x400
	global_load_lds_dwordx4 v[128:129], off
	s_mov_b32 m0, s58
	s_nop 0
	global_load_lds_dwordx4 v[130:131], off

; template <int MASK, int PASS>
; DI void run_tiles_b(Flash& st, const bf16x8 (&qf)[4], const BSrc& src, const int* list, int n, char* kvbuf, int qpos,
;                     int qmin_w, int qmax_w, const OnFn onfn, const float* lut, float bfar, float* imp_row, float rinv) {
;     ...
;     for (int i = 0; i < n; i += 2) {
;         {
;             tileb_store(RA, kvbuf, kvbuf + 8192);
;             __syncthreads();
;             const int pos0 = list[i];
;             if (i + 2 < n) tileb_issue(RA, src, list[i + 2]);
;             tile_step<MASK, PASS>(st, qf, kvbuf, kvbuf + 8192, pos0, qpos, qmin_w, qmax_w, onfn, lut, bfar, imp_row, rinv);
.LBB0_1364:
	v_mov_b32_e32 v2, s16
	ds_read_b32 v182, v2
	ds_read_b32 v183, v2 offset:4
	s_waitcnt vmcnt(0)
	s_waitcnt lgkmcnt(0)
	s_barrier
	s_add_i32 s21, s17, -1
	v_readfirstlane_b32 s22, v182
	s_add_i32 s0, s17, -2
	s_cmp_ge_i32 s0, s20
	s_cbranch_scc1 .LBB0_1366
	v_add_u32_e32 v120, v183, v118
	v_add_u32_e32 v122, v183, v119
	v_med3_i32 v120, v120, 0, v214
	v_med3_i32 v122, v122, 0, v214
	v_lshlrev_b32_e32 v120, 7, v120
	v_lshlrev_b32_e32 v122, 7, v122
	v_mov_b32_e32 v121, 0
	v_mov_b32_e32 v123, 0
	v_lshl_add_u64 v[124:125], v[110:111], 0, v[120:121]
	v_lshl_add_u64 v[126:127], v[112:113], 0, v[122:123]
	v_lshl_add_u64 v[128:129], v[114:115], 0, v[120:121]
	v_lshl_add_u64 v[130:131], v[114:115], 0, v[122:123]
	s_mov_b32 m0, s28
	s_add_i32 s58, s28, 0x400
	global_load_lds_dwordx4 v[124:125], off
	s_mov_b32 m0, s58
	s_nop 0
	global_load_lds_dwordx4 v[126:127], off
	s_mov_b32 m0, s32
	s_add_i32 s58, s32, 0x400
	global_load_lds_dwordx4 v[128:129], off
	s_mov_b32 m0, s58
	s_nop 0
	global_load_lds_dwordx4 v[130:131], off

; template <int MASK, int PASS>
; DI void run_tiles_b(Flash& st, const bf16x8 (&qf)[4], const BSrc& src, const int* list, int n, char* kvbuf, int qpos,
;                     int qmin_w, int qmax_w, const OnFn onfn, const float* lut, float bfar, float* imp_row, float rinv) {
;     ...
;         if (i + 1 < n) {
;             tileb_store(RB, kvbuf + 16384, kvbuf + 24576);
;             __syncthreads();
;             const int pos0 = list[i + 1];
;             if (i + 3 < n) tileb_issue(RB, src, list[i + 3]);
;             tile_step<MASK, PASS>(st, qf, kvbuf + 16384, kvbuf + 24576, pos0, qpos, qmin_w, qmax_w, onfn, lut, bfar, imp_row, rinv);
.LBB0_1372:
	s_add_i32 s0, s17, -2
	s_cmp_ge_i32 s0, s20
	s_cbranch_scc1 .LBB0_1363
	v_mov_b32_e32 v2, s16
	ds_read_b32 v182, v2 offset:4
	ds_read_b32 v183, v2 offset:8
	s_waitcnt vmcnt(0)
	s_waitcnt lgkmcnt(0)
	s_barrier
	v_readfirstlane_b32 s22, v182
	s_cmp_ge_i32 s21, s20
	s_cbranch_scc1 .LBB0_1375
	v_add_u32_e32 v120, v183, v118
	v_add_u32_e32 v122, v183, v119
	v_med3_i32 v120, v120, 0, v214
	v_med3_i32 v122, v122, 0, v214
	v_lshlrev_b32_e32 v120, 7, v120
	v_lshlrev_b32_e32 v122, 7, v122
	v_mov_b32_e32 v121, 0
	v_mov_b32_e32 v123, 0
	v_lshl_add_u64 v[124:125], v[110:111], 0, v[120:121]
	v_lshl_add_u64 v[126:127], v[112:113], 0, v[122:123]
	v_lshl_add_u64 v[128:129], v[114:115], 0, v[120:121]
	v_lshl_add_u64 v[130:131], v[114:115], 0, v[122:123]
	s_mov_b32 m0, s24
	s_add_i32 s58, s24, 0x400
	global_load_lds_dwordx4 v[124:125], off
	s_mov_b32 m0, s58
	s_nop 0
	global_load_lds_dwordx4 v[126:127], off
	s_mov_b32 m0, s26
	s_add_i32 s58, s26, 0x400
	global_load_lds_dwordx4 v[128:129], off
	s_mov_b32 m0, s58
	s_nop 0
	global_load_lds_dwordx4 v[130:131], off

; DI int opaque(int v) { asm volatile("" : "+v"(v)); return v; }
; DI f32x16 zero16() { f32x16 z; for (int i = 0; i < 16; ++i) z[i] = 0.f; return z; }
; template <class AL>
; DI void gemm_mainloop(f32x16 (&acc)[2][2], GemmRegs<AL>& G, bool pre, const AL& al, const u16* __restrict__ Bt, int ldb, int n0, int nk, char* sm,
;                       bool has_next, const AL& aln, int n0n) {
;     const int t = opaque(threadIdx.x), lane = t & 63, w = t >> 6;
;     const int wm = w >> 1, wn = w & 1, r = lane & 31, h = lane >> 5;
;     const int lrow = t >> 3, lch = t & 7;
;     typename AL::Raw& RA0 = G.RA0; typename AL::Raw& RA1 = G.RA1;
;     bf16x8 (&RB0)[4] = G.RB0; bf16x8 (&RB1)[4] = G.RB1;
;     const u16* bp = Bt + (size_t)(n0 + lrow) * ldb + lch * 8;
;     const u16* bpn = Bt + (size_t)(n0n + lrow) * ldb + lch * 8;
;     auto loadB = [&](bf16x8 (&rb)[4], int kt) {
; #pragma unroll
;         for (int i = 0; i < 4; ++i) rb[i] = *(const bf16x8*)(bp + (size_t)(32 * i) * ldb + kt * 64);
;     };
;     auto loadBn = [&](bf16x8 (&rb)[4], int kt) {
; #pragma unroll
;         for (int i = 0; i < 4; ++i) rb[i] = *(const bf16x8*)(bpn + (size_t)(32 * i) * ldb + kt * 64);
;     };
;     auto store = [&](const typename AL::Raw& RA, const bf16x8 (&rb)[4], int kt, char* dA) {
;         bf16x8 ra[4];
;         al.cvt(RA, ra, AL::kmap(kt));
; #pragma unroll
;         for (int i = 0; i < 4; ++i) {
;             const int row = lrow + 32 * i;
;             const int off = row * 128 + ((lch ^ ((row >> 1) & 7)) << 4);
;             *(bf16x8*)(dA + off) = ra[i];
;             *(bf16x8*)(dA + 16384 + off) = rb[i];
;         }
;     };
;     auto compute = [&](const char* cA) {
;         const char* cB = cA + 16384;
;         bf16x8 a[2][2], b[2][2];
;         auto rd = [&](int set, int ks) {
; #pragma unroll
; template <bool SMP>
; DI void gemm2_tile(const Params& p, GemmRegs<ALoadBf16>& G, bool pre, int tm, int tn, bool has_next, int tmn, int tnn, char* sm) {
;     f32x16 acc[2][2];
; #pragma unroll
;     for (int a = 0; a < 2; ++a)
; #pragma unroll
;         for (int b = 0; b < 2; ++b) acc[a][b] = zero16();
;     ALoadBf16 al{(const u16*)(p.ws + WS_MIXED), 1024, tm * 128};
;     ALoadBf16 aln{(const u16*)(p.ws + WS_MIXED), 1024, tmn * 128};
;     gemm_mainloop(acc, G, pre, al, (const u16*)(p.ws + WS_WTOUT), 1024, tn * 128, 16, sm, has_next, aln, tnn * 128);
.LBB0_1610:
	s_add_i32 s93, s30, s44
	s_cmpk_gt_u32 s93, 0x7f
	s_cselect_b64 s[24:25], -1, 0
	s_cmp_lg_u64 s[0:1], 0
	s_cselect_b32 s34, 0x80, 0
	v_readlane_b32 s38, v254, 11
	v_readlane_b32 s39, v254, 12
	s_lshl_b32 s73, s30, 18
	s_add_u32 s73, s73, s34
	s_add_u32 s26, s42, s73
	s_addc_u32 s27, s43, 0
	s_lshl_b32 s73, s45, 11
	s_add_u32 s73, s73, s34
	s_add_u32 s28, s38, s73
	s_addc_u32 s29, s39, 0
	v_lshrrev_b32_e32 v202, 6, v0
	v_and_b32_e32 v194, 63, v0
	v_readfirstlane_b32 s72, v202
	v_lshrrev_b32_e32 v195, 3, v194
	v_and_b32_e32 v196, 7, v194
	v_lshrrev_b32_e32 v197, 1, v195
	v_xor_b32_e32 v198, v196, v197
	v_xor_b32_e32 v199, 4, v198
	v_lshl_add_u32 v200, v202, 5, v195
	v_lshlrev_b32_e32 v201, 11, v200
	v_lshl_add_u32 v190, v198, 4, v201
	v_lshl_add_u32 v191, v199, 4, v201
	v_add_u32_e32 v191, 0x3c00, v191
	v_add_u32_e32 v192, 0x7800, v190
	v_add_u32_e32 v193, 0x7800, v191
	s_lshl_b32 s68, s72, 12
	s_add_i32 s69, s68, 0x4000
	s_add_i32 s70, s68, 0x8000
	s_add_i32 s71, s68, 0xc000
	s_cmp_lg_u32 s34, 0
	s_cbranch_scc1 .Lg5_pre
	s_mov_b32 m0, s68
	s_nop 0
	global_load_lds_dwordx4 v190, s[26:27]
	global_load_lds_dwordx4 v191, s[26:27] offset:1024
	global_load_lds_dwordx4 v192, s[26:27] offset:2048
	global_load_lds_dwordx4 v193, s[26:27] offset:3072
	s_add_u32 s26, s26, 0x80
	s_addc_u32 s27, s27, 0
	s_mov_b32 m0, s69
	s_nop 0
	global_load_lds_dwordx4 v190, s[28:29]
	global_load_lds_dwordx4 v191, s[28:29] offset:1024
	global_load_lds_dwordx4 v192, s[28:29] offset:2048
	global_load_lds_dwordx4 v193, s[28:29] offset:3072
	s_add_u32 s28, s28, 0x80
	s_addc_u32 s29, s29, 0
.Lg5_pre:
	v_bfe_u32 v206, v0, 5, 1
	v_lshlrev_b32_e32 v203, 6, v0
	v_and_b32_e32 v203, 0xffffe000, v203
	v_lshlrev_b32_e32 v204, 7, v0
	s_movk_i32 s35, 0xf80
	v_and_or_b32 v203, v204, s35, v203
	v_add_u32_e32 v222, 0, v203
	v_lshrrev_b32_e32 v203, 1, v0
	v_bitop3_b32 v203, v203, v206, 7 bitop3:0x6c
	v_bfe_u32 v205, v0, 1, 3
	v_lshlrev_b32_e32 v223, 4, v203
	v_and_b32_e32 v203, 0x2f80, v204
	v_add_u32_e32 v224, 0, v203
	v_bitop3_b32 v203, v206, v205, 2 bitop3:0x36
	v_lshlrev_b32_e32 v225, 4, v203
	v_bitop3_b32 v203, v206, v205, 4 bitop3:0x36
	v_lshlrev_b32_e32 v226, 4, v203
	v_bitop3_b32 v203, v206, v205, 6 bitop3:0x36
	v_lshlrev_b32_e32 v227, 4, v203
	v_mov_b32_e32 v2, 0
	v_mov_b32_e32 v3, v2
	v_mov_b32_e32 v4, v2
	v_mov_b32_e32 v5, v2
	v_mov_b32_e32 v6, v2
	v_mov_b32_e32 v7, v2
	v_mov_b32_e32 v8, v2
	v_mov_b32_e32 v9, v2
	v_mov_b32_e32 v10, v2
	v_mov_b32_e32 v11, v2
	v_mov_b32_e32 v12, v2
	v_mov_b32_e32 v13, v2
	v_mov_b32_e32 v14, v2
	v_mov_b32_e32 v15, v2
	v_mov_b32_e32 v16, v2
	v_mov_b32_e32 v17, v2
	v_mov_b32_e32 v18, v2
	v_mov_b32_e32 v19, v2
	v_mov_b32_e32 v20, v2
	v_mov_b32_e32 v21, v2
	v_mov_b32_e32 v22, v2
	v_mov_b32_e32 v23, v2
	v_mov_b32_e32 v24, v2
	v_mov_b32_e32 v25, v2
	v_mov_b32_e32 v26, v2
	v_mov_b32_e32 v27, v2
	v_mov_b32_e32 v28, v2
	v_mov_b32_e32 v29, v2
	v_mov_b32_e32 v30, v2
	v_mov_b32_e32 v31, v2
	v_mov_b32_e32 v32, v2
	v_mov_b32_e32 v33, v2
	v_mov_b32_e32 v34, v2
	v_mov_b32_e32 v35, v2
	v_mov_b32_e32 v36, v2
	v_mov_b32_e32 v37, v2
	v_mov_b32_e32 v38, v2
	v_mov_b32_e32 v39, v2
	v_mov_b32_e32 v40, v2
	v_mov_b32_e32 v41, v2
	v_mov_b32_e32 v42, v2
	v_mov_b32_e32 v43, v2
	v_mov_b32_e32 v44, v2
	v_mov_b32_e32 v45, v2
	v_mov_b32_e32 v46, v2
	v_mov_b32_e32 v47, v2
	v_mov_b32_e32 v48, v2
	v_mov_b32_e32 v49, v2
	v_mov_b32_e32 v50, v2
	v_mov_b32_e32 v51, v2
	v_mov_b32_e32 v52, v2
	v_mov_b32_e32 v53, v2
	v_mov_b32_e32 v54, v2
	v_mov_b32_e32 v55, v2
	v_mov_b32_e32 v56, v2
	v_mov_b32_e32 v57, v2
	v_mov_b32_e32 v58, v2
	v_mov_b32_e32 v59, v2
	v_mov_b32_e32 v60, v2
	v_mov_b32_e32 v61, v2
	v_mov_b32_e32 v62, v2
	v_mov_b32_e32 v63, v2
	v_mov_b32_e32 v64, v2
	v_mov_b32_e32 v65, v2
	s_mov_b32 s32, 0
	s_cmp_lg_u32 s34, 0
	s_cbranch_scc1 .Lg5_prebar
	s_waitcnt vmcnt(0)
.Lg5_prebar:
	s_barrier
; DI f32x16 mfma32(bf16x8 a, bf16x8 b, f32x16 c) { return __builtin_amdgcn_mfma_f32_32x32x16_bf16(a, b, c, 0, 0, 0); }
;     static DI int kmap(int kt) { return (kt >> 1) + 16 * (kt & 1); }
; template <class AL>
; DI void gemm_mainloop(f32x16 (&acc)[2][2], GemmRegs<AL>& G, bool pre, const AL& al, const u16* __restrict__ Bt, int ldb, int n0, int nk, char* sm,
;                       bool has_next, const AL& aln, int n0n) {
;     ...
;     auto compute = [&](const char* cA) {
;         const char* cB = cA + 16384;
;         bf16x8 a[2][2], b[2][2];
;         auto rd = [&](int set, int ks) {
; #pragma unroll
;             for (int mi = 0; mi < 2; ++mi) { const int row = wm * 64 + mi * 32 + r; a[set][mi] = *(const bf16x8*)(cA + row * 128 + (((2 * ks + h) ^ ((row >> 1) & 7)) << 4)); }
; #pragma unroll
;             for (int ni = 0; ni < 2; ++ni) { const int row = wn * 64 + ni * 32 + r; b[set][ni] = *(const bf16x8*)(cB + row * 128 + (((2 * ks + h) ^ ((row >> 1) & 7)) << 4)); }
;         };
;         auto mm = [&](int set) {
; #pragma unroll
;             for (int mi = 0; mi < 2; ++mi)
; #pragma unroll
;                 for (int ni = 0; ni < 2; ++ni) acc[mi][ni] = mfma32(a[set][mi], b[set][ni], acc[mi][ni]);
;         };
;         rd(0, 0); rd(1, 1);
;         __builtin_amdgcn_sched_barrier(0);
;         mm(0); rd(0, 2);
;         __builtin_amdgcn_sched_barrier(0);
;         mm(1); rd(1, 3);
;         __builtin_amdgcn_sched_barrier(0);
;         mm(0); mm(1);
;     };
;     ...
;     for (int kt = 0; kt < nk; kt += 2) {
;         compute(buf0);
;         store(RA1, RB1, kt + 1, buf1);
;         if (kt + 3 < nk) { al.load(RA1, AL::kmap(kt + 3)); loadB(RB1, AL::kmap(kt + 3)); }
;         else if (has_next) { aln.load(RA1, AL::kmap(1)); loadBn(RB1, AL::kmap(1)); }
;         __syncthreads();
;         compute(buf1);
;         if (kt + 2 < nk) {
;             store(RA0, RB0, kt + 2, buf0);
;             if (kt + 4 < nk) { al.load(RA0, AL::kmap(kt + 4)); loadB(RB0, AL::kmap(kt + 4)); }
;             else if (has_next) { aln.load(RA0, AL::kmap(0)); loadBn(RB0, AL::kmap(0)); }
;         }
;         __syncthreads();
;     }
.Lg5_loop:
	v_add_u32_e32 v228, v222, v223
	v_add_u32_e32 v229, v224, v223
	v_add_u32_e32 v230, v222, v225
	v_add_u32_e32 v231, v224, v225
	ds_read_b128 v[204:207], v228
	ds_read_b128 v[208:211], v228 offset:4096
	ds_read_b128 v[212:215], v229 offset:16384
	ds_read_b128 v[216:219], v229 offset:20480
	ds_read_b128 v[234:237], v230
	ds_read_b128 v[238:241], v230 offset:4096
	ds_read_b128 v[242:245], v231 offset:16384
	ds_read_b128 v[246:249], v231 offset:20480
	s_mov_b32 m0, s70
	s_nop 0
	global_load_lds_dwordx4 v190, s[26:27]
	global_load_lds_dwordx4 v191, s[26:27] offset:1024
	global_load_lds_dwordx4 v192, s[26:27] offset:2048
	global_load_lds_dwordx4 v193, s[26:27] offset:3072
	s_add_u32 s26, s26, 0x80
	s_addc_u32 s27, s27, 0
	s_waitcnt lgkmcnt(5)
	v_mfma_f32_32x32x16_bf16 v[50:65], v[204:207], v[212:215], v[50:65]
	v_add_u32_e32 v232, v222, v226
	v_add_u32_e32 v233, v224, v226
	s_waitcnt lgkmcnt(4)
	v_mfma_f32_32x32x16_bf16 v[34:49], v[204:207], v[216:219], v[34:49]
	v_mfma_f32_32x32x16_bf16 v[18:33], v[208:211], v[212:215], v[18:33]
	v_mfma_f32_32x32x16_bf16 v[2:17], v[208:211], v[216:219], v[2:17]
	ds_read_b128 v[204:207], v232
	ds_read_b128 v[208:211], v232 offset:4096
	ds_read_b128 v[212:215], v233 offset:16384
	ds_read_b128 v[216:219], v233 offset:20480
	s_mov_b32 m0, s71
	s_nop 0
	global_load_lds_dwordx4 v190, s[28:29]
	global_load_lds_dwordx4 v191, s[28:29] offset:1024
	global_load_lds_dwordx4 v192, s[28:29] offset:2048
	global_load_lds_dwordx4 v193, s[28:29] offset:3072
	s_add_u32 s28, s28, 0x80
	s_addc_u32 s29, s29, 0
	s_waitcnt lgkmcnt(5)
	v_mfma_f32_32x32x16_bf16 v[50:65], v[234:237], v[242:245], v[50:65]
	s_waitcnt lgkmcnt(4)
	v_mfma_f32_32x32x16_bf16 v[34:49], v[234:237], v[246:249], v[34:49]
	v_add_u32_e32 v234, v222, v227
	v_add_u32_e32 v235, v224, v227
	v_mfma_f32_32x32x16_bf16 v[18:33], v[238:241], v[242:245], v[18:33]
	v_mfma_f32_32x32x16_bf16 v[2:17], v[238:241], v[246:249], v[2:17]
	ds_read_b128 v[236:239], v234
	ds_read_b128 v[240:243], v234 offset:4096
	ds_read_b128 v[244:247], v235 offset:16384
	ds_read_b128 v[248:251], v235 offset:20480
	s_waitcnt lgkmcnt(5)
	v_mfma_f32_32x32x16_bf16 v[50:65], v[204:207], v[212:215], v[50:65]
	s_waitcnt lgkmcnt(4)
	v_mfma_f32_32x32x16_bf16 v[34:49], v[204:207], v[216:219], v[34:49]
	v_mfma_f32_32x32x16_bf16 v[18:33], v[208:211], v[212:215], v[18:33]
	v_mfma_f32_32x32x16_bf16 v[2:17], v[208:211], v[216:219], v[2:17]
	s_waitcnt lgkmcnt(1)
	v_mfma_f32_32x32x16_bf16 v[50:65], v[236:239], v[244:247], v[50:65]
	s_waitcnt lgkmcnt(0)
	v_mfma_f32_32x32x16_bf16 v[34:49], v[236:239], v[248:251], v[34:49]
	v_mfma_f32_32x32x16_bf16 v[18:33], v[240:243], v[244:247], v[18:33]
	v_mfma_f32_32x32x16_bf16 v[2:17], v[240:243], v[248:251], v[2:17]
	s_waitcnt vmcnt(0)
	s_barrier
	s_mov_b32 s34, 1
	s_cmp_lt_u32 s32, 14
	s_cbranch_scc1 .Lg5_bgo
	s_mov_b32 s34, 0
	s_and_b64 vcc, exec, s[24:25]
	s_cbranch_vccnz .Lg5_bgo
	s_mov_b32 s34, 1
	s_lshl_b32 s73, s93, 18
	s_add_u32 s26, s42, s73
	s_addc_u32 s27, s43, 0
	s_lshl_b32 s73, s45, 11
	s_add_u32 s28, s38, s73
	s_addc_u32 s29, s39, 0
.Lg5_bgo:
	ds_read_b128 v[204:207], v228 offset:32768
	ds_read_b128 v[208:211], v228 offset:36864
	ds_read_b128 v[212:215], v229 offset:49152
	ds_read_b128 v[216:219], v229 offset:53248
	ds_read_b128 v[236:239], v230 offset:32768
	ds_read_b128 v[240:243], v230 offset:36864
	ds_read_b128 v[244:247], v231 offset:49152
	ds_read_b128 v[228:231], v231 offset:53248
	s_cmp_eq_u32 s34, 0
	s_cbranch_scc1 .Lg5_skipA
	s_mov_b32 m0, s68
	s_nop 0
	global_load_lds_dwordx4 v190, s[26:27]
	global_load_lds_dwordx4 v191, s[26:27] offset:1024
	global_load_lds_dwordx4 v192, s[26:27] offset:2048
	global_load_lds_dwordx4 v193, s[26:27] offset:3072
	s_add_u32 s26, s26, 0x80
	s_addc_u32 s27, s27, 0
.Lg5_skipA:
	s_waitcnt lgkmcnt(5)
	v_mfma_f32_32x32x16_bf16 v[50:65], v[204:207], v[212:215], v[50:65]
	s_waitcnt lgkmcnt(4)
	v_mfma_f32_32x32x16_bf16 v[34:49], v[204:207], v[216:219], v[34:49]
	v_mfma_f32_32x32x16_bf16 v[18:33], v[208:211], v[212:215], v[18:33]
	v_mfma_f32_32x32x16_bf16 v[2:17], v[208:211], v[216:219], v[2:17]
	ds_read_b128 v[204:207], v232 offset:32768
	ds_read_b128 v[208:211], v232 offset:36864
	ds_read_b128 v[212:215], v233 offset:49152
	ds_read_b128 v[216:219], v233 offset:53248
	s_cmp_eq_u32 s34, 0
	s_cbranch_scc1 .Lg5_skipB
	s_mov_b32 m0, s69
	s_nop 0
	global_load_lds_dwordx4 v190, s[28:29]
	global_load_lds_dwordx4 v191, s[28:29] offset:1024
	global_load_lds_dwordx4 v192, s[28:29] offset:2048
	global_load_lds_dwordx4 v193, s[28:29] offset:3072
	s_add_u32 s28, s28, 0x80
	s_addc_u32 s29, s29, 0
.Lg5_skipB:
	s_waitcnt lgkmcnt(5)
	v_mfma_f32_32x32x16_bf16 v[50:65], v[236:239], v[244:247], v[50:65]
	s_waitcnt lgkmcnt(4)
	v_mfma_f32_32x32x16_bf16 v[34:49], v[236:239], v[228:231], v[34:49]
	v_mfma_f32_32x32x16_bf16 v[18:33], v[240:243], v[244:247], v[18:33]
	v_mfma_f32_32x32x16_bf16 v[2:17], v[240:243], v[228:231], v[2:17]
	ds_read_b128 v[228:231], v234 offset:32768
	ds_read_b128 v[236:239], v234 offset:36864
	ds_read_b128 v[240:243], v235 offset:49152
	ds_read_b128 v[232:235], v235 offset:53248
	s_waitcnt lgkmcnt(5)
	v_mfma_f32_32x32x16_bf16 v[50:65], v[204:207], v[212:215], v[50:65]
	s_waitcnt lgkmcnt(4)
	v_mfma_f32_32x32x16_bf16 v[34:49], v[204:207], v[216:219], v[34:49]
	v_mfma_f32_32x32x16_bf16 v[18:33], v[208:211], v[212:215], v[18:33]
	v_mfma_f32_32x32x16_bf16 v[2:17], v[208:211], v[216:219], v[2:17]
	s_waitcnt lgkmcnt(1)
	v_mfma_f32_32x32x16_bf16 v[50:65], v[228:231], v[240:243], v[50:65]
	s_waitcnt lgkmcnt(0)
	v_mfma_f32_32x32x16_bf16 v[34:49], v[228:231], v[232:235], v[34:49]
	v_mfma_f32_32x32x16_bf16 v[18:33], v[236:239], v[240:243], v[18:33]
	v_mfma_f32_32x32x16_bf16 v[2:17], v[236:239], v[232:235], v[2:17]
	s_waitcnt vmcnt(0)
	s_barrier
	s_add_i32 s32, s32, 2
	s_cmp_lt_u32 s32, 16
	s_cbranch_scc1 .Lg5_loop
